# K-loop head labels aligned to 64 bytes (.p2align 6) on top of k12: code-placement check
# speedup vs baseline: 1.0055x; 1.0029x over previous
; template <class Epi>
; __device__ __forceinline__ void gemm_phase(LAS unsigned char* lds, const int tid, const Gemm g, const StaticOrder& S, const Epi& E) {
;     ...
;         const bool has_next = S.next(ui + 1, nxt);
;         const char* nA = has_next ? (const char*)g.A + (size_t)nxt.pm * tstepA : cA; const char* nB = has_next ? (const char*)g.Bt + (size_t)nxt.pn * tstepB : cB;
;         for (int t = 0; t < nt; t += 2) {
;     ...
; #pragma unroll
;         for (int a = 0; a < 2; ++a)
; #pragma unroll
;             for (int b = 0; b < 2; ++b)
; #pragma unroll
;                 for (int m = 0; m < 4; ++m)
; #pragma unroll
;                     for (int n = 0; n < 2; ++n) acc[a][b][m][n] = (f32x4){0.f, 0.f, 0.f, 0.f};
;         cur = nxt; cA = nA; cB = nB; ++ui;
.LBB0_413:
	s_ashr_i32 s7, s6, 31
	v_readlane_b32 s36, v249, 8
	s_lshl_b64 s[16:17], s[6:7], 19
	v_readlane_b32 s50, v249, 22
	v_readlane_b32 s51, v249, 23
	s_add_u32 s26, s50, s16
	s_addc_u32 s27, s51, s17
	s_and_b64 s[16:17], s[62:63], exec
	s_cselect_b32 s7, s27, s69
	s_cselect_b32 s67, s26, s68
	s_ashr_i32 s5, s4, 31
	s_lshl_b64 s[16:17], s[4:5], 19
	v_readlane_b32 s0, v249, 24
	v_readlane_b32 s1, v249, 25
	s_add_u32 s30, s0, s16
	s_addc_u32 s31, s1, s17
	s_and_b64 s[16:17], s[62:63], exec
	s_cselect_b32 s5, s31, s71
	s_cselect_b32 vcc_lo, s30, s70
	s_add_u32 s68, s68, 0x40080
	s_addc_u32 s69, s69, 0
	v_readlane_b32 s37, v249, 9
	s_add_u32 vcc_hi, s70, 0x100
	v_mov_b32_e32 v2, 0
	s_addc_u32 s76, s71, 0
	s_mov_b32 s16, -2
	v_mov_b32_e32 v3, v2
	v_mov_b32_e32 v4, v2
	v_mov_b32_e32 v5, v2
	v_mov_b32_e32 v6, v2
	v_mov_b32_e32 v7, v2
	v_mov_b32_e32 v8, v2
	v_mov_b32_e32 v9, v2
	v_mov_b32_e32 v18, v2
	v_mov_b32_e32 v19, v2
	v_mov_b32_e32 v20, v2
	v_mov_b32_e32 v21, v2
	v_mov_b32_e32 v22, v2
	v_mov_b32_e32 v23, v2
	v_mov_b32_e32 v24, v2
	v_mov_b32_e32 v25, v2
	v_mov_b32_e32 v34, v2
	v_mov_b32_e32 v35, v2
	v_mov_b32_e32 v36, v2
	v_mov_b32_e32 v37, v2
	v_mov_b32_e32 v38, v2
	v_mov_b32_e32 v39, v2
	v_mov_b32_e32 v40, v2
	v_mov_b32_e32 v41, v2
	v_mov_b32_e32 v58, v2
	v_mov_b32_e32 v59, v2
	v_mov_b32_e32 v60, v2
	v_mov_b32_e32 v61, v2
	v_mov_b32_e32 v62, v2
	v_mov_b32_e32 v63, v2
	v_mov_b32_e32 v64, v2
	v_mov_b32_e32 v65, v2
	v_mov_b32_e32 v10, v2
	v_mov_b32_e32 v11, v2
	v_mov_b32_e32 v12, v2
	v_mov_b32_e32 v13, v2
	v_mov_b32_e32 v14, v2
	v_mov_b32_e32 v15, v2
	v_mov_b32_e32 v16, v2
	v_mov_b32_e32 v17, v2
	v_mov_b32_e32 v26, v2
	v_mov_b32_e32 v27, v2
	v_mov_b32_e32 v28, v2
	v_mov_b32_e32 v29, v2
	v_mov_b32_e32 v30, v2
	v_mov_b32_e32 v31, v2
	v_mov_b32_e32 v32, v2
	v_mov_b32_e32 v33, v2
	v_mov_b32_e32 v42, v2
	v_mov_b32_e32 v43, v2
	v_mov_b32_e32 v44, v2
	v_mov_b32_e32 v45, v2
	v_mov_b32_e32 v46, v2
	v_mov_b32_e32 v47, v2
	v_mov_b32_e32 v48, v2
	v_mov_b32_e32 v49, v2
	v_mov_b32_e32 v74, v2
	v_mov_b32_e32 v75, v2
	v_mov_b32_e32 v76, v2
	v_mov_b32_e32 v77, v2
	v_mov_b32_e32 v78, v2
	v_mov_b32_e32 v79, v2
	v_mov_b32_e32 v80, v2
	v_mov_b32_e32 v81, v2
	v_mov_b32_e32 v82, v2
	v_mov_b32_e32 v83, v2
	v_mov_b32_e32 v84, v2
	v_mov_b32_e32 v85, v2
	v_mov_b32_e32 v86, v2
	v_mov_b32_e32 v87, v2
	v_mov_b32_e32 v88, v2
	v_mov_b32_e32 v89, v2
	v_mov_b32_e32 v98, v2
	v_mov_b32_e32 v99, v2
	s_waitcnt vmcnt(0)
	v_mov_b32_e32 v100, v2
	v_mov_b32_e32 v101, v2
	v_mov_b32_e32 v102, v2
	v_mov_b32_e32 v103, v2
	v_mov_b32_e32 v104, v2
	v_mov_b32_e32 v105, v2
	v_mov_b32_e32 v114, v2
	v_mov_b32_e32 v115, v2
	v_mov_b32_e32 v116, v2
	v_mov_b32_e32 v117, v2
	v_mov_b32_e32 v118, v2
	v_mov_b32_e32 v119, v2
	v_mov_b32_e32 v120, v2
	v_mov_b32_e32 v121, v2
	v_mov_b32_e32 v130, v2
	v_mov_b32_e32 v131, v2
	v_mov_b32_e32 v132, v2
	v_mov_b32_e32 v133, v2
	v_mov_b32_e32 v134, v2
	v_mov_b32_e32 v135, v2
	v_mov_b32_e32 v136, v2
	v_mov_b32_e32 v137, v2
	v_mov_b32_e32 v90, v2
	v_mov_b32_e32 v91, v2
	v_mov_b32_e32 v92, v2
	v_mov_b32_e32 v93, v2
	v_mov_b32_e32 v94, v2
	v_mov_b32_e32 v95, v2
	v_mov_b32_e32 v96, v2
	v_mov_b32_e32 v97, v2
	v_mov_b32_e32 v106, v2
	v_mov_b32_e32 v107, v2
	v_mov_b32_e32 v108, v2
	v_mov_b32_e32 v109, v2
	v_mov_b32_e32 v110, v2
	v_mov_b32_e32 v111, v2
	v_mov_b32_e32 v112, v2
	v_mov_b32_e32 v113, v2
	v_mov_b32_e32 v122, v2
	v_mov_b32_e32 v123, v2
	v_mov_b32_e32 v124, v2
	v_mov_b32_e32 v125, v2
	v_mov_b32_e32 v126, v2
	v_mov_b32_e32 v127, v2
	v_mov_b32_e32 v128, v2
	v_mov_b32_e32 v129, v2
	v_mov_b32_e32 v138, v2
	v_mov_b32_e32 v139, v2
	v_mov_b32_e32 v140, v2
	v_mov_b32_e32 v141, v2
	v_mov_b32_e32 v142, v2
	v_mov_b32_e32 v143, v2
	v_mov_b32_e32 v144, v2
	v_mov_b32_e32 v145, v2
	s_mov_b64 s[36:37], 0x80
	v_readlane_b32 s38, v249, 10
	v_readlane_b32 s39, v249, 11
	v_readlane_b32 s40, v249, 12
	v_readlane_b32 s41, v249, 13
	v_readlane_b32 s42, v249, 14
	v_readlane_b32 s43, v249, 15
	v_readlane_b32 s44, v249, 16
	v_readlane_b32 s45, v249, 17
	v_readlane_b32 s46, v249, 18
	v_readlane_b32 s47, v249, 19
	v_readlane_b32 s48, v249, 20
	v_readlane_b32 s49, v249, 21
	.p2align	6

; template <class Epi>
; __device__ __forceinline__ void gemm_phase(LAS unsigned char* lds, const int tid, const Gemm g, const StaticOrder& S, const Epi& E) {
;     ...
;         const bool has_next = S.next(ui + 1, nxt);
;         const char* nA = has_next ? (const char*)g.A + (size_t)nxt.pm * tstepA : cA; const char* nB = has_next ? (const char*)g.Bt + (size_t)nxt.pn * tstepB : cB;
;         for (int t = 0; t < nt; t += 2) {
;     ...
; #pragma unroll
;         for (int a = 0; a < 2; ++a)
; #pragma unroll
;             for (int b = 0; b < 2; ++b)
; #pragma unroll
;                 for (int m = 0; m < 4; ++m)
; #pragma unroll
;                     for (int n = 0; n < 2; ++n) acc[a][b][m][n] = (f32x4){0.f, 0.f, 0.f, 0.f};
;         cur = nxt; cA = nA; cB = nB; ++ui;
.LBB0_944:
	s_ashr_i32 s27, s26, 31
	v_readlane_b32 s36, v249, 8
	s_lshl_b64 s[66:67], s[26:27], 19
	v_readlane_b32 s50, v249, 22
	v_readlane_b32 s51, v249, 23
	s_add_u32 s66, s50, s66
	s_addc_u32 s67, s51, s67
	s_and_b64 s[68:69], s[62:63], exec
	s_cselect_b32 s9, s67, s73
	s_cselect_b32 s27, s66, s72
	s_ashr_i32 s7, s6, 31
	s_lshl_b64 s[68:69], s[6:7], 19
	v_readlane_b32 s0, v252, 16
	s_add_u32 s68, s0, s68
	v_readlane_b32 s0, v252, 17
	s_addc_u32 s69, s0, s69
	s_and_b64 s[74:75], s[62:63], exec
	s_cselect_b32 s7, s69, s31
	s_cselect_b32 s28, s68, s30
	s_add_u32 s72, s72, 0x40080
	s_addc_u32 s73, s73, 0
	v_readlane_b32 s37, v249, 9
	s_add_u32 s65, s30, 0x100
	v_mov_b32_e32 v2, 0
	s_addc_u32 vcc_lo, s31, 0
	s_mov_b32 vcc_hi, -2
	v_mov_b32_e32 v3, v2
	v_mov_b32_e32 v4, v2
	v_mov_b32_e32 v5, v2
	v_mov_b32_e32 v6, v2
	v_mov_b32_e32 v7, v2
	v_mov_b32_e32 v8, v2
	v_mov_b32_e32 v9, v2
	v_mov_b32_e32 v34, v2
	v_mov_b32_e32 v35, v2
	v_mov_b32_e32 v36, v2
	v_mov_b32_e32 v37, v2
	v_mov_b32_e32 v38, v2
	v_mov_b32_e32 v39, v2
	v_mov_b32_e32 v40, v2
	v_mov_b32_e32 v41, v2
	v_mov_b32_e32 v50, v2
	v_mov_b32_e32 v51, v2
	v_mov_b32_e32 v52, v2
	v_mov_b32_e32 v53, v2
	v_mov_b32_e32 v54, v2
	v_mov_b32_e32 v55, v2
	v_mov_b32_e32 v56, v2
	v_mov_b32_e32 v57, v2
	v_mov_b32_e32 v66, v2
	v_mov_b32_e32 v67, v2
	v_mov_b32_e32 v68, v2
	v_mov_b32_e32 v69, v2
	v_mov_b32_e32 v70, v2
	v_mov_b32_e32 v71, v2
	v_mov_b32_e32 v72, v2
	v_mov_b32_e32 v73, v2
	v_mov_b32_e32 v10, v2
	v_mov_b32_e32 v11, v2
	v_mov_b32_e32 v12, v2
	v_mov_b32_e32 v13, v2
	v_mov_b32_e32 v14, v2
	v_mov_b32_e32 v15, v2
	v_mov_b32_e32 v16, v2
	v_mov_b32_e32 v17, v2
	v_mov_b32_e32 v42, v2
	v_mov_b32_e32 v43, v2
	v_mov_b32_e32 v44, v2
	v_mov_b32_e32 v45, v2
	v_mov_b32_e32 v46, v2
	v_mov_b32_e32 v47, v2
	v_mov_b32_e32 v48, v2
	v_mov_b32_e32 v49, v2
	v_mov_b32_e32 v58, v2
	v_mov_b32_e32 v59, v2
	v_mov_b32_e32 v60, v2
	v_mov_b32_e32 v61, v2
	v_mov_b32_e32 v62, v2
	v_mov_b32_e32 v63, v2
	v_mov_b32_e32 v64, v2
	v_mov_b32_e32 v65, v2
	v_mov_b32_e32 v74, v2
	v_mov_b32_e32 v75, v2
	v_mov_b32_e32 v76, v2
	v_mov_b32_e32 v77, v2
	v_mov_b32_e32 v78, v2
	v_mov_b32_e32 v79, v2
	v_mov_b32_e32 v80, v2
	v_mov_b32_e32 v81, v2
	v_mov_b32_e32 v82, v2
	v_mov_b32_e32 v83, v2
	v_mov_b32_e32 v84, v2
	v_mov_b32_e32 v85, v2
	v_mov_b32_e32 v86, v2
	v_mov_b32_e32 v87, v2
	v_mov_b32_e32 v88, v2
	v_mov_b32_e32 v89, v2
	v_mov_b32_e32 v98, v2
	v_mov_b32_e32 v99, v2
	s_waitcnt vmcnt(0)
	v_mov_b32_e32 v100, v2
	v_mov_b32_e32 v101, v2
	v_mov_b32_e32 v102, v2
	v_mov_b32_e32 v103, v2
	v_mov_b32_e32 v104, v2
	v_mov_b32_e32 v105, v2
	v_mov_b32_e32 v114, v2
	v_mov_b32_e32 v115, v2
	v_mov_b32_e32 v116, v2
	v_mov_b32_e32 v117, v2
	v_mov_b32_e32 v118, v2
	v_mov_b32_e32 v119, v2
	v_mov_b32_e32 v120, v2
	v_mov_b32_e32 v121, v2
	v_mov_b32_e32 v130, v2
	v_mov_b32_e32 v131, v2
	v_mov_b32_e32 v132, v2
	v_mov_b32_e32 v133, v2
	v_mov_b32_e32 v134, v2
	v_mov_b32_e32 v135, v2
	v_mov_b32_e32 v136, v2
	v_mov_b32_e32 v137, v2
	v_mov_b32_e32 v90, v2
	v_mov_b32_e32 v91, v2
	v_mov_b32_e32 v92, v2
	v_mov_b32_e32 v93, v2
	v_mov_b32_e32 v94, v2
	v_mov_b32_e32 v95, v2
	v_mov_b32_e32 v96, v2
	v_mov_b32_e32 v97, v2
	v_mov_b32_e32 v106, v2
	v_mov_b32_e32 v107, v2
	v_mov_b32_e32 v108, v2
	v_mov_b32_e32 v109, v2
	v_mov_b32_e32 v110, v2
	v_mov_b32_e32 v111, v2
	v_mov_b32_e32 v112, v2
	v_mov_b32_e32 v113, v2
	v_mov_b32_e32 v122, v2
	v_mov_b32_e32 v123, v2
	v_mov_b32_e32 v124, v2
	v_mov_b32_e32 v125, v2
	v_mov_b32_e32 v126, v2
	v_mov_b32_e32 v127, v2
	v_mov_b32_e32 v128, v2
	v_mov_b32_e32 v129, v2
	v_mov_b32_e32 v138, v2
	v_mov_b32_e32 v139, v2
	v_mov_b32_e32 v140, v2
	v_mov_b32_e32 v141, v2
	v_mov_b32_e32 v142, v2
	v_mov_b32_e32 v143, v2
	v_mov_b32_e32 v144, v2
	v_mov_b32_e32 v145, v2
	s_mov_b64 s[36:37], 0x80
	v_readlane_b32 s38, v249, 10
	v_readlane_b32 s39, v249, 11
	v_readlane_b32 s40, v249, 12
	v_readlane_b32 s41, v249, 13
	v_readlane_b32 s42, v249, 14
	v_readlane_b32 s43, v249, 15
	v_readlane_b32 s44, v249, 16
	v_readlane_b32 s45, v249, 17
	v_readlane_b32 s46, v249, 18
	v_readlane_b32 s47, v249, 19
	v_readlane_b32 s48, v249, 20
	v_readlane_b32 s49, v249, 21
	.p2align	6

; template <class Epi>
; __device__ __forceinline__ void gemm_phase(LAS unsigned char* lds, const int tid, const Gemm g, const StaticOrder& S, const Epi& E) {
;     ...
;         const bool has_next = S.next(ui + 1, nxt);
;         const char* nA = has_next ? (const char*)g.A + (size_t)nxt.pm * tstepA : cA; const char* nB = has_next ? (const char*)g.Bt + (size_t)nxt.pn * tstepB : cB;
;         for (int t = 0; t < nt; t += 2) {
;     ...
; #pragma unroll
;         for (int a = 0; a < 2; ++a)
; #pragma unroll
;             for (int b = 0; b < 2; ++b)
; #pragma unroll
;                 for (int m = 0; m < 4; ++m)
; #pragma unroll
;                     for (int n = 0; n < 2; ++n) acc[a][b][m][n] = (f32x4){0.f, 0.f, 0.f, 0.f};
;         cur = nxt; cA = nA; cB = nB; ++ui;
.LBB0_1283:
	s_ashr_i32 s11, s10, 31
	s_lshl_b64 s[16:17], s[10:11], 20
	v_readlane_b32 s0, v254, 19
	v_readlane_b32 s1, v254, 20
	s_add_u32 s16, s0, s16
	s_addc_u32 s17, s1, s17
	s_and_b64 s[26:27], s[64:65], exec
	s_cselect_b32 s11, s17, s67
	s_cselect_b32 s88, s16, s66
	s_ashr_i32 s9, s8, 31
	s_lshl_b64 s[26:27], s[8:9], 19
	v_readlane_b32 s0, v254, 15
	v_readlane_b32 s1, v254, 16
	s_add_u32 s26, s0, s26
	s_addc_u32 s27, s1, s27
	s_and_b64 s[68:69], s[64:65], exec
	s_cselect_b32 s9, s27, s31
	s_cselect_b32 s89, s26, s30
	s_add_u32 s66, s66, 0x80080
	s_addc_u32 s67, s67, 0
	s_add_u32 s92, s30, 0x100
	v_mov_b32_e32 v2, 0
	s_addc_u32 s93, s31, 0
	s_mov_b32 vcc_lo, -2
	v_mov_b32_e32 v3, v2
	v_mov_b32_e32 v4, v2
	v_mov_b32_e32 v5, v2
	v_mov_b32_e32 v6, v2
	v_mov_b32_e32 v7, v2
	v_mov_b32_e32 v8, v2
	v_mov_b32_e32 v9, v2
	v_mov_b32_e32 v10, v2
	v_mov_b32_e32 v11, v2
	v_mov_b32_e32 v12, v2
	v_mov_b32_e32 v13, v2
	v_mov_b32_e32 v18, v2
	v_mov_b32_e32 v19, v2
	v_mov_b32_e32 v20, v2
	v_mov_b32_e32 v21, v2
	v_mov_b32_e32 v34, v2
	v_mov_b32_e32 v35, v2
	v_mov_b32_e32 v36, v2
	v_mov_b32_e32 v37, v2
	v_mov_b32_e32 v38, v2
	v_mov_b32_e32 v39, v2
	v_mov_b32_e32 v40, v2
	v_mov_b32_e32 v41, v2
	v_mov_b32_e32 v42, v2
	v_mov_b32_e32 v43, v2
	v_mov_b32_e32 v44, v2
	v_mov_b32_e32 v45, v2
	v_mov_b32_e32 v50, v2
	v_mov_b32_e32 v51, v2
	v_mov_b32_e32 v52, v2
	v_mov_b32_e32 v53, v2
	v_mov_b32_e32 v14, v2
	v_mov_b32_e32 v15, v2
	v_mov_b32_e32 v16, v2
	v_mov_b32_e32 v17, v2
	v_mov_b32_e32 v22, v2
	v_mov_b32_e32 v23, v2
	v_mov_b32_e32 v24, v2
	v_mov_b32_e32 v25, v2
	v_mov_b32_e32 v26, v2
	v_mov_b32_e32 v27, v2
	v_mov_b32_e32 v28, v2
	v_mov_b32_e32 v29, v2
	v_mov_b32_e32 v30, v2
	v_mov_b32_e32 v31, v2
	v_mov_b32_e32 v32, v2
	v_mov_b32_e32 v33, v2
	v_mov_b32_e32 v46, v2
	v_mov_b32_e32 v47, v2
	v_mov_b32_e32 v48, v2
	v_mov_b32_e32 v49, v2
	v_mov_b32_e32 v54, v2
	v_mov_b32_e32 v55, v2
	v_mov_b32_e32 v56, v2
	v_mov_b32_e32 v57, v2
	v_mov_b32_e32 v58, v2
	v_mov_b32_e32 v59, v2
	v_mov_b32_e32 v60, v2
	v_mov_b32_e32 v61, v2
	v_mov_b32_e32 v62, v2
	v_mov_b32_e32 v63, v2
	v_mov_b32_e32 v64, v2
	v_mov_b32_e32 v65, v2
	v_mov_b32_e32 v66, v2
	v_mov_b32_e32 v67, v2
	v_mov_b32_e32 v68, v2
	v_mov_b32_e32 v69, v2
	v_mov_b32_e32 v70, v2
	v_mov_b32_e32 v71, v2
	v_mov_b32_e32 v72, v2
	v_mov_b32_e32 v73, v2
	v_mov_b32_e32 v74, v2
	v_mov_b32_e32 v75, v2
	v_mov_b32_e32 v76, v2
	v_mov_b32_e32 v77, v2
	v_mov_b32_e32 v82, v2
	v_mov_b32_e32 v83, v2
	v_mov_b32_e32 v84, v2
	v_mov_b32_e32 v85, v2
	v_mov_b32_e32 v98, v2
	v_mov_b32_e32 v99, v2
	s_waitcnt vmcnt(0)
	v_mov_b32_e32 v100, v2
	v_mov_b32_e32 v101, v2
	v_mov_b32_e32 v102, v2
	v_mov_b32_e32 v103, v2
	v_mov_b32_e32 v104, v2
	v_mov_b32_e32 v105, v2
	v_mov_b32_e32 v106, v2
	v_mov_b32_e32 v107, v2
	v_mov_b32_e32 v108, v2
	v_mov_b32_e32 v109, v2
	v_mov_b32_e32 v114, v2
	v_mov_b32_e32 v115, v2
	v_mov_b32_e32 v116, v2
	v_mov_b32_e32 v117, v2
	v_mov_b32_e32 v78, v2
	v_mov_b32_e32 v79, v2
	v_mov_b32_e32 v80, v2
	v_mov_b32_e32 v81, v2
	v_mov_b32_e32 v86, v2
	v_mov_b32_e32 v87, v2
	v_mov_b32_e32 v88, v2
	v_mov_b32_e32 v89, v2
	v_mov_b32_e32 v90, v2
	v_mov_b32_e32 v91, v2
	v_mov_b32_e32 v92, v2
	v_mov_b32_e32 v93, v2
	v_mov_b32_e32 v94, v2
	v_mov_b32_e32 v95, v2
	v_mov_b32_e32 v96, v2
	v_mov_b32_e32 v97, v2
	v_mov_b32_e32 v110, v2
	v_mov_b32_e32 v111, v2
	v_mov_b32_e32 v112, v2
	v_mov_b32_e32 v113, v2
	v_mov_b32_e32 v118, v2
	v_mov_b32_e32 v119, v2
	v_mov_b32_e32 v120, v2
	v_mov_b32_e32 v121, v2
	v_mov_b32_e32 v122, v2
	v_mov_b32_e32 v123, v2
	v_mov_b32_e32 v124, v2
	v_mov_b32_e32 v125, v2
	v_mov_b32_e32 v126, v2
	v_mov_b32_e32 v127, v2
	v_mov_b32_e32 v128, v2
	v_mov_b32_e32 v129, v2
	s_mov_b64 s[36:37], 0x80
	.p2align	6

; template <class Epi>
; __device__ __forceinline__ void gemm_phase(LAS unsigned char* lds, const int tid, const Gemm g, const StaticOrder& S, const Epi& E) {
;     ...
;         const bool has_next = S.next(ui + 1, nxt);
;         const char* nA = has_next ? (const char*)g.A + (size_t)nxt.pm * tstepA : cA; const char* nB = has_next ? (const char*)g.Bt + (size_t)nxt.pn * tstepB : cB;
;         for (int t = 0; t < nt; t += 2) {
;     ...
; #pragma unroll
;         for (int a = 0; a < 2; ++a)
; #pragma unroll
;             for (int b = 0; b < 2; ++b)
; #pragma unroll
;                 for (int m = 0; m < 4; ++m)
; #pragma unroll
;                     for (int n = 0; n < 2; ++n) acc[a][b][m][n] = (f32x4){0.f, 0.f, 0.f, 0.f};
;         cur = nxt; cA = nA; cB = nB; ++ui;
.LBB0_1332:
	s_ashr_i32 s11, s10, 31
	s_lshl_b64 s[2:3], s[10:11], 20
	v_readlane_b32 s0, v254, 33
	v_readlane_b32 s1, v254, 34
	s_add_u32 s16, s0, s2
	s_addc_u32 s17, s1, s3
	s_and_b64 s[2:3], s[62:63], exec
	s_cselect_b32 s11, s17, s67
	s_cselect_b32 s88, s16, s66
	s_ashr_i32 s9, s8, 31
	s_lshl_b64 s[2:3], s[8:9], 19
	v_readlane_b32 s0, v254, 29
	v_readlane_b32 s1, v254, 30
	s_add_u32 s26, s0, s2
	s_addc_u32 s27, s1, s3
	s_and_b64 s[2:3], s[62:63], exec
	s_cselect_b32 s9, s27, s31
	s_cselect_b32 s89, s26, s30
	s_add_u32 s66, s66, 0x80080
	s_addc_u32 s67, s67, 0
	s_add_u32 s92, s30, 0x100
	v_mov_b32_e32 v2, 0
	s_addc_u32 s93, s31, 0
	s_mov_b32 vcc_lo, -2
	v_mov_b32_e32 v3, v2
	v_mov_b32_e32 v4, v2
	v_mov_b32_e32 v5, v2
	v_mov_b32_e32 v6, v2
	v_mov_b32_e32 v7, v2
	v_mov_b32_e32 v8, v2
	v_mov_b32_e32 v9, v2
	v_mov_b32_e32 v18, v2
	v_mov_b32_e32 v19, v2
	v_mov_b32_e32 v20, v2
	v_mov_b32_e32 v21, v2
	v_mov_b32_e32 v22, v2
	v_mov_b32_e32 v23, v2
	v_mov_b32_e32 v24, v2
	v_mov_b32_e32 v25, v2
	v_mov_b32_e32 v34, v2
	v_mov_b32_e32 v35, v2
	v_mov_b32_e32 v36, v2
	v_mov_b32_e32 v37, v2
	v_mov_b32_e32 v38, v2
	v_mov_b32_e32 v39, v2
	v_mov_b32_e32 v40, v2
	v_mov_b32_e32 v41, v2
	v_mov_b32_e32 v50, v2
	v_mov_b32_e32 v51, v2
	v_mov_b32_e32 v52, v2
	v_mov_b32_e32 v53, v2
	v_mov_b32_e32 v54, v2
	v_mov_b32_e32 v55, v2
	v_mov_b32_e32 v56, v2
	v_mov_b32_e32 v57, v2
	v_mov_b32_e32 v10, v2
	v_mov_b32_e32 v11, v2
	v_mov_b32_e32 v12, v2
	v_mov_b32_e32 v13, v2
	v_mov_b32_e32 v14, v2
	v_mov_b32_e32 v15, v2
	v_mov_b32_e32 v16, v2
	v_mov_b32_e32 v17, v2
	v_mov_b32_e32 v26, v2
	v_mov_b32_e32 v27, v2
	v_mov_b32_e32 v28, v2
	v_mov_b32_e32 v29, v2
	v_mov_b32_e32 v30, v2
	v_mov_b32_e32 v31, v2
	v_mov_b32_e32 v32, v2
	v_mov_b32_e32 v33, v2
	v_mov_b32_e32 v42, v2
	v_mov_b32_e32 v43, v2
	v_mov_b32_e32 v44, v2
	v_mov_b32_e32 v45, v2
	v_mov_b32_e32 v46, v2
	v_mov_b32_e32 v47, v2
	v_mov_b32_e32 v48, v2
	v_mov_b32_e32 v49, v2
	v_mov_b32_e32 v58, v2
	v_mov_b32_e32 v59, v2
	v_mov_b32_e32 v60, v2
	v_mov_b32_e32 v61, v2
	v_mov_b32_e32 v62, v2
	v_mov_b32_e32 v63, v2
	v_mov_b32_e32 v64, v2
	v_mov_b32_e32 v65, v2
	v_mov_b32_e32 v66, v2
	v_mov_b32_e32 v67, v2
	v_mov_b32_e32 v68, v2
	v_mov_b32_e32 v69, v2
	v_mov_b32_e32 v70, v2
	v_mov_b32_e32 v71, v2
	v_mov_b32_e32 v72, v2
	v_mov_b32_e32 v73, v2
	v_mov_b32_e32 v82, v2
	v_mov_b32_e32 v83, v2
	v_mov_b32_e32 v84, v2
	v_mov_b32_e32 v85, v2
	v_mov_b32_e32 v86, v2
	v_mov_b32_e32 v87, v2
	v_mov_b32_e32 v88, v2
	v_mov_b32_e32 v89, v2
	v_mov_b32_e32 v98, v2
	v_mov_b32_e32 v99, v2
	s_waitcnt vmcnt(0)
	v_mov_b32_e32 v100, v2
	v_mov_b32_e32 v101, v2
	v_mov_b32_e32 v102, v2
	v_mov_b32_e32 v103, v2
	v_mov_b32_e32 v104, v2
	v_mov_b32_e32 v105, v2
	v_mov_b32_e32 v114, v2
	v_mov_b32_e32 v115, v2
	v_mov_b32_e32 v116, v2
	v_mov_b32_e32 v117, v2
	v_mov_b32_e32 v118, v2
	v_mov_b32_e32 v119, v2
	v_mov_b32_e32 v120, v2
	v_mov_b32_e32 v121, v2
	v_mov_b32_e32 v74, v2
	v_mov_b32_e32 v75, v2
	v_mov_b32_e32 v76, v2
	v_mov_b32_e32 v77, v2
	v_mov_b32_e32 v78, v2
	v_mov_b32_e32 v79, v2
	v_mov_b32_e32 v80, v2
	v_mov_b32_e32 v81, v2
	v_mov_b32_e32 v90, v2
	v_mov_b32_e32 v91, v2
	v_mov_b32_e32 v92, v2
	v_mov_b32_e32 v93, v2
	v_mov_b32_e32 v94, v2
	v_mov_b32_e32 v95, v2
	v_mov_b32_e32 v96, v2
	v_mov_b32_e32 v97, v2
	v_mov_b32_e32 v106, v2
	v_mov_b32_e32 v107, v2
	v_mov_b32_e32 v108, v2
	v_mov_b32_e32 v109, v2
	v_mov_b32_e32 v110, v2
	v_mov_b32_e32 v111, v2
	v_mov_b32_e32 v112, v2
	v_mov_b32_e32 v113, v2
	v_mov_b32_e32 v122, v2
	v_mov_b32_e32 v123, v2
	v_mov_b32_e32 v124, v2
	v_mov_b32_e32 v125, v2
	v_mov_b32_e32 v126, v2
	v_mov_b32_e32 v127, v2
	v_mov_b32_e32 v128, v2
	v_mov_b32_e32 v129, v2
	s_mov_b64 s[36:37], 0x80
	.p2align	6

; template <class Epi>
; __device__ __forceinline__ void gemm_phase(LAS unsigned char* lds, const int tid, const Gemm g, const StaticOrder& S, const Epi& E) {
;     ...
;         const bool has_next = S.next(ui + 1, nxt);
;         const char* nA = has_next ? (const char*)g.A + (size_t)nxt.pm * tstepA : cA; const char* nB = has_next ? (const char*)g.Bt + (size_t)nxt.pn * tstepB : cB;
;         for (int t = 0; t < nt; t += 2) {
;     ...
; #pragma unroll
;         for (int a = 0; a < 2; ++a)
; #pragma unroll
;             for (int b = 0; b < 2; ++b)
; #pragma unroll
;                 for (int m = 0; m < 4; ++m)
; #pragma unroll
;                     for (int n = 0; n < 2; ++n) acc[a][b][m][n] = (f32x4){0.f, 0.f, 0.f, 0.f};
;         cur = nxt; cA = nA; cB = nB; ++ui;
.LBB0_1486:
	s_ashr_i32 s83, s82, 31
	s_lshl_b64 s[26:27], s[82:83], 19
	s_add_u32 s92, s60, s26
	s_addc_u32 s93, s61, s27
	s_and_b64 s[26:27], s[66:67], exec
	s_cselect_b32 s28, s93, s69
	s_cselect_b32 s71, s92, s68
	s_ashr_i32 s5, s4, 31
	s_lshl_b64 s[26:27], s[4:5], 19
	v_readlane_b32 s36, v252, 26
	v_readlane_b32 s37, v252, 27
	s_add_u32 s76, s36, s26
	s_addc_u32 s77, s37, s27
	s_and_b64 s[26:27], s[66:67], exec
	s_cselect_b32 s5, s77, s31
	s_cselect_b32 s73, s76, s30
	s_add_u32 s68, s68, 0x40080
	s_addc_u32 s69, s69, 0
	s_add_u32 s75, s30, 0x100
	v_mov_b32_e32 v2, 0
	s_addc_u32 s83, s31, 0
	s_mov_b32 s26, -2
	s_waitcnt lgkmcnt(0)
	v_mov_b32_e32 v3, v2
	v_mov_b32_e32 v4, v2
	v_mov_b32_e32 v5, v2
	v_mov_b32_e32 v6, v2
	v_mov_b32_e32 v7, v2
	v_mov_b32_e32 v8, v2
	v_mov_b32_e32 v9, v2
	v_mov_b32_e32 v18, v2
	v_mov_b32_e32 v19, v2
	v_mov_b32_e32 v20, v2
	v_mov_b32_e32 v21, v2
	v_mov_b32_e32 v22, v2
	v_mov_b32_e32 v23, v2
	v_mov_b32_e32 v24, v2
	v_mov_b32_e32 v25, v2
	v_mov_b32_e32 v34, v2
	v_mov_b32_e32 v35, v2
	v_mov_b32_e32 v36, v2
	v_mov_b32_e32 v37, v2
	v_mov_b32_e32 v38, v2
	v_mov_b32_e32 v39, v2
	v_mov_b32_e32 v40, v2
	v_mov_b32_e32 v41, v2
	v_mov_b32_e32 v50, v2
	v_mov_b32_e32 v51, v2
	v_mov_b32_e32 v52, v2
	v_mov_b32_e32 v53, v2
	v_mov_b32_e32 v54, v2
	v_mov_b32_e32 v55, v2
	v_mov_b32_e32 v56, v2
	v_mov_b32_e32 v57, v2
	v_mov_b32_e32 v10, v2
	v_mov_b32_e32 v11, v2
	v_mov_b32_e32 v12, v2
	v_mov_b32_e32 v13, v2
	v_mov_b32_e32 v14, v2
	v_mov_b32_e32 v15, v2
	v_mov_b32_e32 v16, v2
	v_mov_b32_e32 v17, v2
	v_mov_b32_e32 v26, v2
	v_mov_b32_e32 v27, v2
	v_mov_b32_e32 v28, v2
	v_mov_b32_e32 v29, v2
	v_mov_b32_e32 v30, v2
	v_mov_b32_e32 v31, v2
	v_mov_b32_e32 v32, v2
	v_mov_b32_e32 v33, v2
	v_mov_b32_e32 v42, v2
	v_mov_b32_e32 v43, v2
	v_mov_b32_e32 v44, v2
	v_mov_b32_e32 v45, v2
	v_mov_b32_e32 v46, v2
	v_mov_b32_e32 v47, v2
	v_mov_b32_e32 v48, v2
	v_mov_b32_e32 v49, v2
	v_mov_b32_e32 v58, v2
	v_mov_b32_e32 v59, v2
	v_mov_b32_e32 v60, v2
	v_mov_b32_e32 v61, v2
	v_mov_b32_e32 v62, v2
	v_mov_b32_e32 v63, v2
	v_mov_b32_e32 v64, v2
	v_mov_b32_e32 v65, v2
	v_mov_b32_e32 v66, v2
	v_mov_b32_e32 v67, v2
	v_mov_b32_e32 v68, v2
	v_mov_b32_e32 v69, v2
	v_mov_b32_e32 v70, v2
	v_mov_b32_e32 v71, v2
	v_mov_b32_e32 v72, v2
	v_mov_b32_e32 v73, v2
	v_mov_b32_e32 v82, v2
	v_mov_b32_e32 v83, v2
	v_mov_b32_e32 v84, v2
	v_mov_b32_e32 v85, v2
	v_mov_b32_e32 v86, v2
	v_mov_b32_e32 v87, v2
	v_mov_b32_e32 v88, v2
	v_mov_b32_e32 v89, v2
	v_mov_b32_e32 v98, v2
	v_mov_b32_e32 v99, v2
	s_waitcnt vmcnt(0)
	v_mov_b32_e32 v100, v2
	v_mov_b32_e32 v101, v2
	v_mov_b32_e32 v102, v2
	v_mov_b32_e32 v103, v2
	v_mov_b32_e32 v104, v2
	v_mov_b32_e32 v105, v2
	v_mov_b32_e32 v114, v2
	v_mov_b32_e32 v115, v2
	v_mov_b32_e32 v116, v2
	v_mov_b32_e32 v117, v2
	v_mov_b32_e32 v118, v2
	v_mov_b32_e32 v119, v2
	v_mov_b32_e32 v120, v2
	v_mov_b32_e32 v121, v2
	v_mov_b32_e32 v74, v2
	v_mov_b32_e32 v75, v2
	v_mov_b32_e32 v76, v2
	v_mov_b32_e32 v77, v2
	v_mov_b32_e32 v78, v2
	v_mov_b32_e32 v79, v2
	v_mov_b32_e32 v80, v2
	v_mov_b32_e32 v81, v2
	v_mov_b32_e32 v90, v2
	v_mov_b32_e32 v91, v2
	v_mov_b32_e32 v92, v2
	v_mov_b32_e32 v93, v2
	v_mov_b32_e32 v94, v2
	v_mov_b32_e32 v95, v2
	v_mov_b32_e32 v96, v2
	v_mov_b32_e32 v97, v2
	v_mov_b32_e32 v106, v2
	v_mov_b32_e32 v107, v2
	v_mov_b32_e32 v108, v2
	v_mov_b32_e32 v109, v2
	v_mov_b32_e32 v110, v2
	v_mov_b32_e32 v111, v2
	v_mov_b32_e32 v112, v2
	v_mov_b32_e32 v113, v2
	v_mov_b32_e32 v122, v2
	v_mov_b32_e32 v123, v2
	v_mov_b32_e32 v124, v2
	v_mov_b32_e32 v125, v2
	v_mov_b32_e32 v126, v2
	v_mov_b32_e32 v127, v2
	v_mov_b32_e32 v128, v2
	v_mov_b32_e32 v129, v2
	s_mov_b64 s[36:37], 0x80
	.p2align	6

; template <class Epi>
; __device__ __forceinline__ void gemm_phase(LAS unsigned char* lds, const int tid, const Gemm g, const StaticOrder& S, const Epi& E) {
;     ...
;         const bool has_next = S.next(ui + 1, nxt);
;         const char* nA = has_next ? (const char*)g.A + (size_t)nxt.pm * tstepA : cA; const char* nB = has_next ? (const char*)g.Bt + (size_t)nxt.pn * tstepB : cB;
;         for (int t = 0; t < nt; t += 2) {
;     ...
; #pragma unroll
;         for (int a = 0; a < 2; ++a)
; #pragma unroll
;             for (int b = 0; b < 2; ++b)
; #pragma unroll
;                 for (int m = 0; m < 4; ++m)
; #pragma unroll
;                     for (int n = 0; n < 2; ++n) acc[a][b][m][n] = (f32x4){0.f, 0.f, 0.f, 0.f};
;         cur = nxt; cA = nA; cB = nB; ++ui;
.LBB0_1911:
	s_ashr_i32 s7, s6, 31
	v_readlane_b32 s36, v249, 8
	s_lshl_b64 s[74:75], s[6:7], 19
	v_readlane_b32 s50, v249, 22
	v_readlane_b32 s51, v249, 23
	s_add_u32 s74, s50, s74
	s_addc_u32 s75, s51, s75
	s_and_b64 s[76:77], s[62:63], exec
	v_readlane_b32 s37, v249, 9
	s_cselect_b32 s7, s75, s83
	s_cselect_b32 s65, s74, s82
	s_ashr_i32 s5, s4, 31
	s_lshl_b64 s[76:77], s[4:5], 19
	v_readlane_b32 s36, v252, 28
	v_readlane_b32 s37, v252, 29
	s_add_u32 s76, s36, s76
	s_addc_u32 s77, s37, s77
	s_and_b64 s[88:89], s[62:63], exec
	s_cselect_b32 s5, s77, s31
	s_cselect_b32 vcc_lo, s76, s30
	s_add_u32 s82, s82, 0x40080
	s_addc_u32 s83, s83, 0
	s_add_u32 vcc_hi, s30, 0x100
	v_mov_b32_e32 v2, 0
	s_addc_u32 s27, s31, 0
	s_mov_b32 s17, -2
	v_mov_b32_e32 v3, v2
	v_mov_b32_e32 v4, v2
	v_mov_b32_e32 v5, v2
	v_mov_b32_e32 v6, v2
	v_mov_b32_e32 v7, v2
	v_mov_b32_e32 v8, v2
	v_mov_b32_e32 v9, v2
	v_mov_b32_e32 v10, v2
	v_mov_b32_e32 v11, v2
	v_mov_b32_e32 v12, v2
	v_mov_b32_e32 v13, v2
	v_mov_b32_e32 v18, v2
	v_mov_b32_e32 v19, v2
	v_mov_b32_e32 v20, v2
	v_mov_b32_e32 v21, v2
	v_mov_b32_e32 v34, v2
	v_mov_b32_e32 v35, v2
	v_mov_b32_e32 v36, v2
	v_mov_b32_e32 v37, v2
	v_mov_b32_e32 v38, v2
	v_mov_b32_e32 v39, v2
	v_mov_b32_e32 v40, v2
	v_mov_b32_e32 v41, v2
	v_mov_b32_e32 v42, v2
	v_mov_b32_e32 v43, v2
	v_mov_b32_e32 v44, v2
	v_mov_b32_e32 v45, v2
	v_mov_b32_e32 v50, v2
	v_mov_b32_e32 v51, v2
	v_mov_b32_e32 v52, v2
	v_mov_b32_e32 v53, v2
	v_mov_b32_e32 v14, v2
	v_mov_b32_e32 v15, v2
	v_mov_b32_e32 v16, v2
	v_mov_b32_e32 v17, v2
	v_mov_b32_e32 v22, v2
	v_mov_b32_e32 v23, v2
	v_mov_b32_e32 v24, v2
	v_mov_b32_e32 v25, v2
	v_mov_b32_e32 v26, v2
	v_mov_b32_e32 v27, v2
	v_mov_b32_e32 v28, v2
	v_mov_b32_e32 v29, v2
	v_mov_b32_e32 v30, v2
	v_mov_b32_e32 v31, v2
	v_mov_b32_e32 v32, v2
	v_mov_b32_e32 v33, v2
	v_mov_b32_e32 v46, v2
	v_mov_b32_e32 v47, v2
	v_mov_b32_e32 v48, v2
	v_mov_b32_e32 v49, v2
	v_mov_b32_e32 v54, v2
	v_mov_b32_e32 v55, v2
	v_mov_b32_e32 v56, v2
	v_mov_b32_e32 v57, v2
	v_mov_b32_e32 v58, v2
	v_mov_b32_e32 v59, v2
	v_mov_b32_e32 v60, v2
	v_mov_b32_e32 v61, v2
	v_mov_b32_e32 v62, v2
	v_mov_b32_e32 v63, v2
	v_mov_b32_e32 v64, v2
	v_mov_b32_e32 v65, v2
	v_mov_b32_e32 v66, v2
	v_mov_b32_e32 v67, v2
	v_mov_b32_e32 v68, v2
	v_mov_b32_e32 v69, v2
	v_mov_b32_e32 v70, v2
	v_mov_b32_e32 v71, v2
	v_mov_b32_e32 v72, v2
	v_mov_b32_e32 v73, v2
	v_mov_b32_e32 v82, v2
	v_mov_b32_e32 v83, v2
	v_mov_b32_e32 v84, v2
	v_mov_b32_e32 v85, v2
	v_mov_b32_e32 v86, v2
	v_mov_b32_e32 v87, v2
	v_mov_b32_e32 v88, v2
	v_mov_b32_e32 v89, v2
	v_mov_b32_e32 v114, v2
	v_mov_b32_e32 v115, v2
	v_mov_b32_e32 v116, v2
	v_mov_b32_e32 v117, v2
	v_mov_b32_e32 v118, v2
	v_mov_b32_e32 v119, v2
	v_mov_b32_e32 v120, v2
	v_mov_b32_e32 v121, v2
	v_mov_b32_e32 v122, v2
	v_mov_b32_e32 v123, v2
	v_mov_b32_e32 v124, v2
	v_mov_b32_e32 v125, v2
	v_mov_b32_e32 v126, v2
	v_mov_b32_e32 v127, v2
	v_mov_b32_e32 v128, v2
	v_mov_b32_e32 v129, v2
	v_mov_b32_e32 v74, v2
	v_mov_b32_e32 v75, v2
	v_mov_b32_e32 v76, v2
	v_mov_b32_e32 v77, v2
	v_mov_b32_e32 v78, v2
	v_mov_b32_e32 v79, v2
	v_mov_b32_e32 v80, v2
	v_mov_b32_e32 v81, v2
	v_mov_b32_e32 v90, v2
	v_mov_b32_e32 v91, v2
	v_mov_b32_e32 v92, v2
	v_mov_b32_e32 v93, v2
	v_mov_b32_e32 v94, v2
	v_mov_b32_e32 v95, v2
	v_mov_b32_e32 v96, v2
	v_mov_b32_e32 v97, v2
	v_mov_b32_e32 v130, v2
	v_mov_b32_e32 v131, v2
	v_mov_b32_e32 v132, v2
	v_mov_b32_e32 v133, v2
	v_mov_b32_e32 v134, v2
	v_mov_b32_e32 v135, v2
	v_mov_b32_e32 v136, v2
	v_mov_b32_e32 v137, v2
	v_mov_b32_e32 v138, v2
	v_mov_b32_e32 v139, v2
	v_mov_b32_e32 v140, v2
	v_mov_b32_e32 v141, v2
	v_mov_b32_e32 v142, v2
	v_mov_b32_e32 v143, v2
	v_mov_b32_e32 v144, v2
	v_mov_b32_e32 v145, v2
	s_mov_b64 s[36:37], 0x80
	v_readlane_b32 s38, v249, 10
	v_readlane_b32 s39, v249, 11
	v_readlane_b32 s40, v249, 12
	v_readlane_b32 s41, v249, 13
	v_readlane_b32 s42, v249, 14
	v_readlane_b32 s43, v249, 15
	v_readlane_b32 s44, v249, 16
	v_readlane_b32 s45, v249, 17
	v_readlane_b32 s46, v249, 18
	v_readlane_b32 s47, v249, 19
	v_readlane_b32 s48, v249, 20
	v_readlane_b32 s49, v249, 21
	s_waitcnt vmcnt(0)
	.p2align	6

; template <class Epi>
; __device__ __forceinline__ void gemm_phase(LAS unsigned char* lds, const int tid, const Gemm g, const StaticOrder& S, const Epi& E) {
;     ...
;         const bool has_next = S.next(ui + 1, nxt);
;         const char* nA = has_next ? (const char*)g.A + (size_t)nxt.pm * tstepA : cA; const char* nB = has_next ? (const char*)g.Bt + (size_t)nxt.pn * tstepB : cB;
;         for (int t = 0; t < nt; t += 2) {
;     ...
; #pragma unroll
;         for (int a = 0; a < 2; ++a)
; #pragma unroll
;             for (int b = 0; b < 2; ++b)
; #pragma unroll
;                 for (int m = 0; m < 4; ++m)
; #pragma unroll
;                     for (int n = 0; n < 2; ++n) acc[a][b][m][n] = (f32x4){0.f, 0.f, 0.f, 0.f};
;         cur = nxt; cA = nA; cB = nB; ++ui;
.LBB0_2192:
	s_add_u32 s28, s70, 0x100
	v_mov_b32_e32 v2, 0
	s_addc_u32 vcc_lo, s71, 0
	s_mov_b32 vcc_hi, -2
	s_waitcnt lgkmcnt(0)
	v_mov_b32_e32 v3, v2
	v_mov_b32_e32 v4, v2
	v_mov_b32_e32 v5, v2
	v_mov_b32_e32 v6, v2
	v_mov_b32_e32 v7, v2
	v_mov_b32_e32 v8, v2
	v_mov_b32_e32 v9, v2
	v_mov_b32_e32 v18, v2
	v_mov_b32_e32 v19, v2
	v_mov_b32_e32 v20, v2
	v_mov_b32_e32 v21, v2
	v_mov_b32_e32 v22, v2
	v_mov_b32_e32 v23, v2
	v_mov_b32_e32 v24, v2
	v_mov_b32_e32 v25, v2
	v_mov_b32_e32 v34, v2
	v_mov_b32_e32 v35, v2
	v_mov_b32_e32 v36, v2
	v_mov_b32_e32 v37, v2
	v_mov_b32_e32 v38, v2
	v_mov_b32_e32 v39, v2
	v_mov_b32_e32 v40, v2
	v_mov_b32_e32 v41, v2
	v_mov_b32_e32 v50, v2
	v_mov_b32_e32 v51, v2
	v_mov_b32_e32 v52, v2
	v_mov_b32_e32 v53, v2
	v_mov_b32_e32 v54, v2
	v_mov_b32_e32 v55, v2
	v_mov_b32_e32 v56, v2
	v_mov_b32_e32 v57, v2
	v_mov_b32_e32 v10, v2
	v_mov_b32_e32 v11, v2
	v_mov_b32_e32 v12, v2
	v_mov_b32_e32 v13, v2
	v_mov_b32_e32 v14, v2
	v_mov_b32_e32 v15, v2
	v_mov_b32_e32 v16, v2
	v_mov_b32_e32 v17, v2
	v_mov_b32_e32 v26, v2
	v_mov_b32_e32 v27, v2
	v_mov_b32_e32 v28, v2
	v_mov_b32_e32 v29, v2
	v_mov_b32_e32 v30, v2
	v_mov_b32_e32 v31, v2
	v_mov_b32_e32 v32, v2
	v_mov_b32_e32 v33, v2
	v_mov_b32_e32 v42, v2
	v_mov_b32_e32 v43, v2
	v_mov_b32_e32 v44, v2
	v_mov_b32_e32 v45, v2
	v_mov_b32_e32 v46, v2
	v_mov_b32_e32 v47, v2
	v_mov_b32_e32 v48, v2
	v_mov_b32_e32 v49, v2
	v_mov_b32_e32 v58, v2
	v_mov_b32_e32 v59, v2
	v_mov_b32_e32 v60, v2
	v_mov_b32_e32 v61, v2
	v_mov_b32_e32 v62, v2
	v_mov_b32_e32 v63, v2
	v_mov_b32_e32 v64, v2
	v_mov_b32_e32 v65, v2
	v_mov_b32_e32 v66, v2
	v_mov_b32_e32 v67, v2
	v_mov_b32_e32 v68, v2
	v_mov_b32_e32 v69, v2
	v_mov_b32_e32 v70, v2
	v_mov_b32_e32 v71, v2
	v_mov_b32_e32 v72, v2
	v_mov_b32_e32 v73, v2
	v_mov_b32_e32 v82, v2
	v_mov_b32_e32 v83, v2
	v_mov_b32_e32 v84, v2
	v_mov_b32_e32 v85, v2
	v_mov_b32_e32 v86, v2
	v_mov_b32_e32 v87, v2
	v_mov_b32_e32 v88, v2
	v_mov_b32_e32 v89, v2
	v_mov_b32_e32 v98, v2
	v_mov_b32_e32 v99, v2
	s_waitcnt vmcnt(0)
	v_mov_b32_e32 v100, v2
	v_mov_b32_e32 v101, v2
	v_mov_b32_e32 v102, v2
	v_mov_b32_e32 v103, v2
	v_mov_b32_e32 v104, v2
	v_mov_b32_e32 v105, v2
	v_mov_b32_e32 v114, v2
	v_mov_b32_e32 v115, v2
	v_mov_b32_e32 v116, v2
	v_mov_b32_e32 v117, v2
	v_mov_b32_e32 v118, v2
	v_mov_b32_e32 v119, v2
	v_mov_b32_e32 v120, v2
	v_mov_b32_e32 v121, v2
	v_mov_b32_e32 v74, v2
	v_mov_b32_e32 v75, v2
	v_mov_b32_e32 v76, v2
	v_mov_b32_e32 v77, v2
	v_mov_b32_e32 v78, v2
	v_mov_b32_e32 v79, v2
	v_mov_b32_e32 v80, v2
	v_mov_b32_e32 v81, v2
	v_mov_b32_e32 v90, v2
	v_mov_b32_e32 v91, v2
	v_mov_b32_e32 v92, v2
	v_mov_b32_e32 v93, v2
	v_mov_b32_e32 v94, v2
	v_mov_b32_e32 v95, v2
	v_mov_b32_e32 v96, v2
	v_mov_b32_e32 v97, v2
	v_mov_b32_e32 v106, v2
	v_mov_b32_e32 v107, v2
	v_mov_b32_e32 v108, v2
	v_mov_b32_e32 v109, v2
	v_mov_b32_e32 v110, v2
	v_mov_b32_e32 v111, v2
	v_mov_b32_e32 v112, v2
	v_mov_b32_e32 v113, v2
	v_mov_b32_e32 v122, v2
	v_mov_b32_e32 v123, v2
	v_mov_b32_e32 v124, v2
	v_mov_b32_e32 v125, v2
	v_mov_b32_e32 v126, v2
	v_mov_b32_e32 v127, v2
	v_mov_b32_e32 v128, v2
	v_mov_b32_e32 v129, v2
	s_mov_b64 s[36:37], 0x80
	.p2align	6

; template <class Epi>
; __device__ __forceinline__ void gemm_phase(LAS unsigned char* lds, const int tid, const Gemm g, const StaticOrder& S, const Epi& E) {
;     ...
;         const bool has_next = S.next(ui + 1, nxt);
;         const char* nA = has_next ? (const char*)g.A + (size_t)nxt.pm * tstepA : cA; const char* nB = has_next ? (const char*)g.Bt + (size_t)nxt.pn * tstepB : cB;
;         for (int t = 0; t < nt; t += 2) {
;     ...
; #pragma unroll
;         for (int a = 0; a < 2; ++a)
; #pragma unroll
;             for (int b = 0; b < 2; ++b)
; #pragma unroll
;                 for (int m = 0; m < 4; ++m)
; #pragma unroll
;                     for (int n = 0; n < 2; ++n) acc[a][b][m][n] = (f32x4){0.f, 0.f, 0.f, 0.f};
;         cur = nxt; cA = nA; cB = nB; ++ui;
.LBB0_2302:
	s_add_u32 s11, s68, 0x100
	v_mov_b32_e32 v2, 0
	s_addc_u32 s28, s69, 0
	s_mov_b32 s93, -2
	v_mov_b32_e32 v3, v2
	v_mov_b32_e32 v4, v2
	v_mov_b32_e32 v5, v2
	v_mov_b32_e32 v6, v2
	v_mov_b32_e32 v7, v2
	v_mov_b32_e32 v8, v2
	v_mov_b32_e32 v9, v2
	v_mov_b32_e32 v18, v2
	v_mov_b32_e32 v19, v2
	v_mov_b32_e32 v20, v2
	v_mov_b32_e32 v21, v2
	v_mov_b32_e32 v22, v2
	v_mov_b32_e32 v23, v2
	v_mov_b32_e32 v24, v2
	v_mov_b32_e32 v25, v2
	v_mov_b32_e32 v34, v2
	v_mov_b32_e32 v35, v2
	v_mov_b32_e32 v36, v2
	v_mov_b32_e32 v37, v2
	v_mov_b32_e32 v38, v2
	v_mov_b32_e32 v39, v2
	v_mov_b32_e32 v40, v2
	v_mov_b32_e32 v41, v2
	v_mov_b32_e32 v58, v2
	v_mov_b32_e32 v59, v2
	v_mov_b32_e32 v60, v2
	v_mov_b32_e32 v61, v2
	v_mov_b32_e32 v62, v2
	v_mov_b32_e32 v63, v2
	v_mov_b32_e32 v64, v2
	v_mov_b32_e32 v65, v2
	v_mov_b32_e32 v10, v2
	v_mov_b32_e32 v11, v2
	v_mov_b32_e32 v12, v2
	v_mov_b32_e32 v13, v2
	v_mov_b32_e32 v14, v2
	v_mov_b32_e32 v15, v2
	v_mov_b32_e32 v16, v2
	v_mov_b32_e32 v17, v2
	v_mov_b32_e32 v26, v2
	v_mov_b32_e32 v27, v2
	v_mov_b32_e32 v28, v2
	v_mov_b32_e32 v29, v2
	v_mov_b32_e32 v30, v2
	v_mov_b32_e32 v31, v2
	v_mov_b32_e32 v32, v2
	v_mov_b32_e32 v33, v2
	v_mov_b32_e32 v50, v2
	v_mov_b32_e32 v51, v2
	v_mov_b32_e32 v52, v2
	v_mov_b32_e32 v53, v2
	v_mov_b32_e32 v54, v2
	v_mov_b32_e32 v55, v2
	v_mov_b32_e32 v56, v2
	v_mov_b32_e32 v57, v2
	v_mov_b32_e32 v74, v2
	v_mov_b32_e32 v75, v2
	v_mov_b32_e32 v76, v2
	v_mov_b32_e32 v77, v2
	v_mov_b32_e32 v78, v2
	v_mov_b32_e32 v79, v2
	v_mov_b32_e32 v80, v2
	v_mov_b32_e32 v81, v2
	v_mov_b32_e32 v82, v2
	v_mov_b32_e32 v83, v2
	v_mov_b32_e32 v84, v2
	v_mov_b32_e32 v85, v2
	v_mov_b32_e32 v86, v2
	v_mov_b32_e32 v87, v2
	v_mov_b32_e32 v88, v2
	v_mov_b32_e32 v89, v2
	v_mov_b32_e32 v98, v2
	v_mov_b32_e32 v99, v2
	s_waitcnt vmcnt(0)
	v_mov_b32_e32 v100, v2
	v_mov_b32_e32 v101, v2
	v_mov_b32_e32 v102, v2
	v_mov_b32_e32 v103, v2
	v_mov_b32_e32 v104, v2
	v_mov_b32_e32 v105, v2
	v_mov_b32_e32 v114, v2
	v_mov_b32_e32 v115, v2
	v_mov_b32_e32 v116, v2
	v_mov_b32_e32 v117, v2
	v_mov_b32_e32 v118, v2
	v_mov_b32_e32 v119, v2
	v_mov_b32_e32 v120, v2
	v_mov_b32_e32 v121, v2
	v_mov_b32_e32 v130, v2
	v_mov_b32_e32 v131, v2
	v_mov_b32_e32 v132, v2
	v_mov_b32_e32 v133, v2
	v_mov_b32_e32 v134, v2
	v_mov_b32_e32 v135, v2
	v_mov_b32_e32 v136, v2
	v_mov_b32_e32 v137, v2
	v_mov_b32_e32 v90, v2
	v_mov_b32_e32 v91, v2
	v_mov_b32_e32 v92, v2
	v_mov_b32_e32 v93, v2
	v_mov_b32_e32 v94, v2
	v_mov_b32_e32 v95, v2
	v_mov_b32_e32 v96, v2
	v_mov_b32_e32 v97, v2
	v_mov_b32_e32 v106, v2
	v_mov_b32_e32 v107, v2
	v_mov_b32_e32 v108, v2
	v_mov_b32_e32 v109, v2
	v_mov_b32_e32 v110, v2
	v_mov_b32_e32 v111, v2
	v_mov_b32_e32 v112, v2
	v_mov_b32_e32 v113, v2
	v_mov_b32_e32 v122, v2
	v_mov_b32_e32 v123, v2
	v_mov_b32_e32 v124, v2
	v_mov_b32_e32 v125, v2
	v_mov_b32_e32 v126, v2
	v_mov_b32_e32 v127, v2
	v_mov_b32_e32 v128, v2
	v_mov_b32_e32 v129, v2
	v_mov_b32_e32 v138, v2
	v_mov_b32_e32 v139, v2
	v_mov_b32_e32 v140, v2
	v_mov_b32_e32 v141, v2
	v_mov_b32_e32 v142, v2
	v_mov_b32_e32 v143, v2
	v_mov_b32_e32 v144, v2
	v_mov_b32_e32 v145, v2
	s_mov_b64 s[36:37], 0x80
	.p2align	6

; template <class Epi>
; __device__ __forceinline__ void gemm_phase(LAS unsigned char* lds, const int tid, const Gemm g, const StaticOrder& S, const Epi& E) {
;     ...
;         const bool has_next = S.next(ui + 1, nxt);
;         const char* nA = has_next ? (const char*)g.A + (size_t)nxt.pm * tstepA : cA; const char* nB = has_next ? (const char*)g.Bt + (size_t)nxt.pn * tstepB : cB;
;         for (int t = 0; t < nt; t += 2) {
;     ...
; #pragma unroll
;         for (int a = 0; a < 2; ++a)
; #pragma unroll
;             for (int b = 0; b < 2; ++b)
; #pragma unroll
;                 for (int m = 0; m < 4; ++m)
; #pragma unroll
;                     for (int n = 0; n < 2; ++n) acc[a][b][m][n] = (f32x4){0.f, 0.f, 0.f, 0.f};
;         cur = nxt; cA = nA; cB = nB; ++ui;
.LBB0_2352:
	s_add_u32 s11, s70, 0x100
	v_mov_b32_e32 v2, 0
	s_addc_u32 vcc_lo, s71, 0
	s_mov_b32 vcc_hi, -2
	s_waitcnt lgkmcnt(0)
	v_mov_b32_e32 v3, v2
	v_mov_b32_e32 v4, v2
	v_mov_b32_e32 v5, v2
	v_mov_b32_e32 v6, v2
	v_mov_b32_e32 v7, v2
	v_mov_b32_e32 v8, v2
	v_mov_b32_e32 v9, v2
	v_mov_b32_e32 v18, v2
	v_mov_b32_e32 v19, v2
	v_mov_b32_e32 v20, v2
	v_mov_b32_e32 v21, v2
	v_mov_b32_e32 v22, v2
	v_mov_b32_e32 v23, v2
	v_mov_b32_e32 v24, v2
	v_mov_b32_e32 v25, v2
	v_mov_b32_e32 v34, v2
	v_mov_b32_e32 v35, v2
	v_mov_b32_e32 v36, v2
	v_mov_b32_e32 v37, v2
	v_mov_b32_e32 v38, v2
	v_mov_b32_e32 v39, v2
	v_mov_b32_e32 v40, v2
	v_mov_b32_e32 v41, v2
	v_mov_b32_e32 v50, v2
	v_mov_b32_e32 v51, v2
	v_mov_b32_e32 v52, v2
	v_mov_b32_e32 v53, v2
	v_mov_b32_e32 v54, v2
	v_mov_b32_e32 v55, v2
	v_mov_b32_e32 v56, v2
	v_mov_b32_e32 v57, v2
	v_mov_b32_e32 v10, v2
	v_mov_b32_e32 v11, v2
	v_mov_b32_e32 v12, v2
	v_mov_b32_e32 v13, v2
	v_mov_b32_e32 v14, v2
	v_mov_b32_e32 v15, v2
	v_mov_b32_e32 v16, v2
	v_mov_b32_e32 v17, v2
	v_mov_b32_e32 v26, v2
	v_mov_b32_e32 v27, v2
	v_mov_b32_e32 v28, v2
	v_mov_b32_e32 v29, v2
	v_mov_b32_e32 v30, v2
	v_mov_b32_e32 v31, v2
	v_mov_b32_e32 v32, v2
	v_mov_b32_e32 v33, v2
	v_mov_b32_e32 v42, v2
	v_mov_b32_e32 v43, v2
	v_mov_b32_e32 v44, v2
	v_mov_b32_e32 v45, v2
	v_mov_b32_e32 v46, v2
	v_mov_b32_e32 v47, v2
	v_mov_b32_e32 v48, v2
	v_mov_b32_e32 v49, v2
	v_mov_b32_e32 v58, v2
	v_mov_b32_e32 v59, v2
	v_mov_b32_e32 v60, v2
	v_mov_b32_e32 v61, v2
	v_mov_b32_e32 v62, v2
	v_mov_b32_e32 v63, v2
	v_mov_b32_e32 v64, v2
	v_mov_b32_e32 v65, v2
	v_mov_b32_e32 v66, v2
	v_mov_b32_e32 v67, v2
	v_mov_b32_e32 v68, v2
	v_mov_b32_e32 v69, v2
	v_mov_b32_e32 v70, v2
	v_mov_b32_e32 v71, v2
	v_mov_b32_e32 v72, v2
	v_mov_b32_e32 v73, v2
	v_mov_b32_e32 v82, v2
	v_mov_b32_e32 v83, v2
	v_mov_b32_e32 v84, v2
	v_mov_b32_e32 v85, v2
	v_mov_b32_e32 v86, v2
	v_mov_b32_e32 v87, v2
	v_mov_b32_e32 v88, v2
	v_mov_b32_e32 v89, v2
	v_mov_b32_e32 v98, v2
	v_mov_b32_e32 v99, v2
	s_waitcnt vmcnt(0)
	v_mov_b32_e32 v100, v2
	v_mov_b32_e32 v101, v2
	v_mov_b32_e32 v102, v2
	v_mov_b32_e32 v103, v2
	v_mov_b32_e32 v104, v2
	v_mov_b32_e32 v105, v2
	v_mov_b32_e32 v114, v2
	v_mov_b32_e32 v115, v2
	v_mov_b32_e32 v116, v2
	v_mov_b32_e32 v117, v2
	v_mov_b32_e32 v118, v2
	v_mov_b32_e32 v119, v2
	v_mov_b32_e32 v120, v2
	v_mov_b32_e32 v121, v2
	v_mov_b32_e32 v74, v2
	v_mov_b32_e32 v75, v2
	v_mov_b32_e32 v76, v2
	v_mov_b32_e32 v77, v2
	v_mov_b32_e32 v78, v2
	v_mov_b32_e32 v79, v2
	v_mov_b32_e32 v80, v2
	v_mov_b32_e32 v81, v2
	v_mov_b32_e32 v90, v2
	v_mov_b32_e32 v91, v2
	v_mov_b32_e32 v92, v2
	v_mov_b32_e32 v93, v2
	v_mov_b32_e32 v94, v2
	v_mov_b32_e32 v95, v2
	v_mov_b32_e32 v96, v2
	v_mov_b32_e32 v97, v2
	v_mov_b32_e32 v106, v2
	v_mov_b32_e32 v107, v2
	v_mov_b32_e32 v108, v2
	v_mov_b32_e32 v109, v2
	v_mov_b32_e32 v110, v2
	v_mov_b32_e32 v111, v2
	v_mov_b32_e32 v112, v2
	v_mov_b32_e32 v113, v2
	v_mov_b32_e32 v122, v2
	v_mov_b32_e32 v123, v2
	v_mov_b32_e32 v124, v2
	v_mov_b32_e32 v125, v2
	v_mov_b32_e32 v126, v2
	v_mov_b32_e32 v127, v2
	v_mov_b32_e32 v128, v2
	v_mov_b32_e32 v129, v2
	s_mov_b64 s[36:37], 0x80
	.p2align	6
